# attention loop: all eight waves run the MFMA-then-softmax role (single code path)
# baseline (speedup 1.0000x reference)
; #define LAS __attribute__((address_space(3)))
; DI void attn_phase(const Params& p, const int layer, const int wid_s) {
;     ...
; #pragma unroll 1
;       for (int br = 1; br <= 2; ++br) {
;         const h16* kbase = hb + (br == 1 ? C_KS : C_KW) + g * 64;
;         const h16* vT = (const h16*)(p.ws + (br == 1 ? OFF_VST : OFF_VWT)) + (size_t)bg * 64 * SEQ;
;         int kb0 = 0, lo_w = 0;
;         if (br == 2) { kb0 = qblk * 64 - 512; if (kb0 < 0) kb0 = 0; lo_w = t0 - 511; if (lo_w < 0) lo_w = 0; lo_w &= ~31; }
;         const int nsteps = (kb_last - kb0) / 32 + 1;
;         f32x4 O[2][4]; float l[2];
; #pragma unroll
;         for (int hp = 0; hp < 2; ++hp) { l[hp] = 0.f;
; #pragma unroll
;           for (int dt = 0; dt < 4; ++dt) O[hp][dt] = (f32x4){0.f, 0.f, 0.f, 0.f}; }
;     ...
;         asm volatile("s_waitcnt vmcnt(0)" ::: "memory");
;         __syncthreads();
;         RING_ISSUE(0); RING_ISSUE(1);
; #pragma unroll 1
;         for (int si = 0; si < nsteps; ++si) {
;           asm volatile("s_waitcnt vmcnt(1) lgkmcnt(0)" ::: "memory");
;           __builtin_amdgcn_s_barrier();
;           asm volatile("" ::: "memory");
;           RING_ISSUE(si + 2);
;           const int kb = kb0 + si * 32;
;           if (kb > kmax_w || kb < lo_w) continue;
;           if (br == 1 && kb + 31 + 128 <= t0 && __ballot((selmask >> (kb >> 6)) & 1u) == 0ull) continue;
;           LAS unsigned char* slotp = ring + (si % 3) * 8192;
;           KF kv;
; #pragma unroll
;           for (int kt = 0; kt < 2; ++kt)
; #pragma unroll
;             for (int ks = 0; ks < 2; ++ks) kv.k[kt][ks] = *(const LAS half8*)(slotp + kread[kt][ks]);
; #pragma unroll
;           for (int dt = 0; dt < 4; ++dt) kv.v[dt] = *(const LAS half8*)(slotp + vread[dt]);
;           if (br == 1) {
;             const bool bit = (selmask >> (kb >> 6)) & 1u;
;             if (kb + 31 + 128 <= t0) attn_step<true, false>(kv, kb, t, lane, bit, tabh, q, O, nRs, l);
;             else attn_step<true, true>(kv, kb, t, lane, bit, tabh, q, O, nRs, l);
;           } else {
;             const bool gen = (kb + 31 + 128 > t0) || (kb + 512 <= t0 + 15);
;             if (!gen) attn_step<false, false>(kv, kb, t, lane, true, tabh, q, O, nRw, l);
;             else attn_step<false, true>(kv, kb, t, lane, true, tabh, q, O, nRw, l);
;           }
;         }
.LBB0_349:
	s_branch .Lat_ytop
